# v85 + early un-waited buffer_wbl2 by wave 1 of every workgroup on reaching a grid-barrier seam, so the XCD leader's mandatory L2 write-back on the barrier critical path finds most lines already clean
# baseline (speedup 1.0000x reference)
; __device__ __forceinline__ unsigned xb_ld(unsigned* p)              { return __hip_atomic_load(p, __ATOMIC_RELAXED, __HIP_MEMORY_SCOPE_AGENT); }
; __device__ __forceinline__ unsigned xb_add(unsigned* p, unsigned v) { return __hip_atomic_fetch_add(p, v, __ATOMIC_RELAXED, __HIP_MEMORY_SCOPE_AGENT); }
; __device__ __forceinline__ void xcd_barrier_complete(unsigned* bar, unsigned x, unsigned& nloc, unsigned& nx) {
;     const unsigned G = gridDim.x * gridDim.y * gridDim.z;
;     unsigned sum, cnt, mine, sp = 0u;
;     for (;;) {
;         sum = 0u; cnt = 0u; mine = 0u;
; #pragma unroll
;         for (unsigned j = 0; j < 16; ++j) { const unsigned c = xb_ld(&bar[XB_XCNT(j)]); sum += c; cnt += (c > 0u) ? 1u : 0u; mine = (j == x) ? c : mine; }
; __device__ __forceinline__ void xcd_barrier(const XcdBarrier& b) {
;     asm volatile("s_waitcnt vmcnt(0)" ::: "memory");
;     __syncthreads();
;     if (threadIdx.x == 0) {
;         unsigned* bar = b.bar;
;         __builtin_amdgcn_s_waitcnt(0);
;         unsigned nloc = b.st[0], nx = b.st[1];
;         if (nloc == 0u) { xcd_barrier_complete(bar, b.x, nloc, nx); b.st[0] = nloc; b.st[1] = nx; }
;         const unsigned old = xb_add(&bar[XB_XSUB(b.x)], 1u);
.LBB0_330:
	v_readlane_b32 s8, v247, 5
	v_readlane_b32 s9, v247, 6
	s_cmp_gt_i32 s9, 3
	s_cselect_b64 s[0:1], -1, 0
	s_and_b64 s[4:5], s[6:7], s[0:1]
	s_andn2_b64 vcc, exec, s[4:5]
	v_readlane_b32 s10, v247, 7
	v_readlane_b32 s11, v247, 8
	s_cbranch_vccnz .LBB0_380
	s_waitcnt vmcnt(0)
	v_cmp_eq_u32_e32 vcc, 0, v212
	s_waitcnt vmcnt(0) lgkmcnt(0)
	s_barrier
	v_readlane_b32 s3, v247, 0
	s_nop 3
	s_cmp_lg_u32 s3, 64
	s_cbranch_scc1 .Lew_0
	buffer_wbl2 sc1
.Lew_0:
	s_and_saveexec_b64 s[4:5], vcc
	s_cbranch_execz .LBB0_379
	s_add_i32 s3, 0, 0x27ff0
	v_mov_b32_e32 v0, s3
	s_waitcnt vmcnt(0) expcnt(0) lgkmcnt(0)
	ds_read_b32 v2, v0
	s_add_i32 s3, 0, 0x27ff4
	v_mov_b32_e32 v0, s3
	ds_read_b32 v0, v0
	s_waitcnt lgkmcnt(1)
	v_cmp_ne_u32_e32 vcc, 0, v2
	s_cbranch_vccnz .LBB0_347
	v_readlane_b32 s6, v247, 1
	v_readlane_b32 s7, v247, 2
	s_load_dwordx2 s[10:11], s[6:7], 0x4
	s_add_u32 s6, s92, 0x700200
	s_addc_u32 s7, s93, 0
	s_add_u32 s8, s92, 0x700400
	s_addc_u32 s9, s93, 0
	s_waitcnt lgkmcnt(0)
	s_mul_i32 s3, s10, s33
	s_add_u32 s10, s92, 0x700500
	s_mul_i32 s3, s3, s11
	s_addc_u32 s11, s93, 0
	s_add_u32 s12, s92, 0x700600
	s_addc_u32 s13, s93, 0
	s_add_u32 s14, s92, 0x700700
	s_addc_u32 s15, s93, 0
	s_add_u32 s16, s92, 0x700800
	s_addc_u32 s17, s93, 0
	s_add_u32 s18, s92, 0x700900
	s_addc_u32 s19, s93, 0
	s_add_u32 s20, s92, 0x700a00
	s_addc_u32 s21, s93, 0
	s_add_u32 s22, s92, 0x700b00
	s_addc_u32 s23, s93, 0
	s_add_u32 s24, s92, 0x700c00
	s_addc_u32 s25, s93, 0
	s_add_u32 s26, s92, 0x700d00
	s_addc_u32 s27, s93, 0
	s_add_u32 s28, s92, 0x700e00
	s_addc_u32 s29, s93, 0
	s_add_u32 s30, s92, 0x700f00
	s_addc_u32 s31, s93, 0
	s_add_u32 s34, s92, 0x701000
	s_addc_u32 s35, s93, 0
	s_add_u32 s40, s92, 0x701100
	s_addc_u32 s41, s93, 0
	s_add_u32 s44, s92, 0x701200
	s_addc_u32 s45, s93, 0
	s_add_u32 s52, s92, 0x701300
	s_addc_u32 s53, s93, 0
	s_mov_b32 s60, 1
	v_mov_b32_e32 v16, 0
	s_branch .LBB0_335

; #define PHASE(k) if (lo <= (k) && (k) < hi)
; #define SEAM(k) if (lo <= (k) && (k) + 1 < hi) { xcd_barrier(xb); }
; __device__ __forceinline__ void xcd_barrier(const XcdBarrier& b) {
;     asm volatile("s_waitcnt vmcnt(0)" ::: "memory");
;     __syncthreads();
;     if (threadIdx.x == 0) {
; __global__ void __launch_bounds__(512, 2) fwd_megakernel(Params prm) {
;     ...
;     PHASE(3) { if (F.bid == 0 && F.tid < 8) WSP(int, WS_SMALL + SM_PROG)[F.tid * 64] = 0; for (int un = F.bid; un < 2048; un += F.G) gdn_local_unit(F, un & 7, un >> 3); s5_wu_phase(F); } SEAM(3)
.LBB0_822:
	v_readlane_b32 s4, v247, 5
	v_readlane_b32 s5, v247, 6
	s_cmp_gt_i32 s5, 4
	s_cselect_b64 s[0:1], -1, 0
	s_and_b64 s[4:5], s[18:19], s[0:1]
	s_andn2_b64 vcc, exec, s[4:5]
	v_readlane_b32 s6, v247, 7
	v_readlane_b32 s7, v247, 8
	s_cbranch_vccnz .LBB0_872
	s_waitcnt vmcnt(0)
	v_cmp_eq_u32_e32 vcc, 0, v212
	s_waitcnt vmcnt(0) lgkmcnt(0)
	s_barrier
	v_readlane_b32 s3, v247, 0
	s_nop 3
	s_cmp_lg_u32 s3, 64
	s_cbranch_scc1 .Lew_1
	buffer_wbl2 sc1

; __device__ __forceinline__ unsigned xb_ld(unsigned* p)              { return __hip_atomic_load(p, __ATOMIC_RELAXED, __HIP_MEMORY_SCOPE_AGENT); }
; __device__ __forceinline__ unsigned xb_add(unsigned* p, unsigned v) { return __hip_atomic_fetch_add(p, v, __ATOMIC_RELAXED, __HIP_MEMORY_SCOPE_AGENT); }
; __device__ __forceinline__ void xcd_barrier_complete(unsigned* bar, unsigned x, unsigned& nloc, unsigned& nx) {
;     const unsigned G = gridDim.x * gridDim.y * gridDim.z;
;     unsigned sum, cnt, mine, sp = 0u;
;     for (;;) {
;         sum = 0u; cnt = 0u; mine = 0u;
; #pragma unroll
;         for (unsigned j = 0; j < 16; ++j) { const unsigned c = xb_ld(&bar[XB_XCNT(j)]); sum += c; cnt += (c > 0u) ? 1u : 0u; mine = (j == x) ? c : mine; }
; __device__ __forceinline__ void xcd_barrier(const XcdBarrier& b) {
;     asm volatile("s_waitcnt vmcnt(0)" ::: "memory");
;     __syncthreads();
;     if (threadIdx.x == 0) {
;         unsigned* bar = b.bar;
;         __builtin_amdgcn_s_waitcnt(0);
;         unsigned nloc = b.st[0], nx = b.st[1];
;         if (nloc == 0u) { xcd_barrier_complete(bar, b.x, nloc, nx); b.st[0] = nloc; b.st[1] = nx; }
;         const unsigned old = xb_add(&bar[XB_XSUB(b.x)], 1u);
.LBB0_1047:
	v_readlane_b32 s4, v247, 5
	v_readlane_b32 s5, v247, 6
	s_cmp_gt_i32 s5, 5
	s_cselect_b64 s[0:1], -1, 0
	s_and_b64 s[4:5], s[10:11], s[0:1]
	s_andn2_b64 vcc, exec, s[4:5]
	v_readlane_b32 s76, v247, 10
	v_readlane_b32 s6, v247, 7
	v_readlane_b32 s7, v247, 8
	v_readlane_b32 s77, v247, 11
	s_cbranch_vccnz .LBB0_1097
	s_waitcnt vmcnt(0)
	v_cmp_eq_u32_e32 vcc, 0, v212
	s_waitcnt vmcnt(0) lgkmcnt(0)
	s_barrier
	v_readlane_b32 s3, v247, 0
	s_nop 3
	s_cmp_lg_u32 s3, 64
	s_cbranch_scc1 .Lew_2
	buffer_wbl2 sc1
.Lew_2:
	s_and_saveexec_b64 s[4:5], vcc
	s_cbranch_execz .LBB0_1096
	s_add_i32 s3, 0, 0x27ff0
	v_mov_b32_e32 v0, s3
	s_waitcnt vmcnt(0) expcnt(0) lgkmcnt(0)
	ds_read_b32 v2, v0
	s_add_i32 s3, 0, 0x27ff4
	v_mov_b32_e32 v0, s3
	ds_read_b32 v0, v0
	s_waitcnt lgkmcnt(1)
	v_cmp_ne_u32_e32 vcc, 0, v2
	s_cbranch_vccnz .LBB0_1064
	v_readlane_b32 s6, v247, 1
	v_readlane_b32 s7, v247, 2
	s_load_dwordx2 s[10:11], s[6:7], 0x4
	s_add_u32 s6, s92, 0x700200
	s_addc_u32 s7, s93, 0
	s_add_u32 s8, s92, 0x700400
	s_addc_u32 s9, s93, 0
	s_waitcnt lgkmcnt(0)
	s_mul_i32 s3, s10, s33
	s_add_u32 s10, s92, 0x700500
	s_mul_i32 s3, s3, s11
	s_addc_u32 s11, s93, 0
	s_add_u32 s12, s92, 0x700600
	s_addc_u32 s13, s93, 0
	s_add_u32 s14, s92, 0x700700
	s_addc_u32 s15, s93, 0
	s_add_u32 s16, s92, 0x700800
	s_addc_u32 s17, s93, 0
	s_add_u32 s18, s92, 0x700900
	s_addc_u32 s19, s93, 0
	s_add_u32 s20, s92, 0x700a00
	s_addc_u32 s21, s93, 0
	s_add_u32 s22, s92, 0x700b00
	s_addc_u32 s23, s93, 0
	s_add_u32 s24, s92, 0x700c00
	s_addc_u32 s25, s93, 0
	s_add_u32 s26, s92, 0x700d00
	s_addc_u32 s27, s93, 0
	s_add_u32 s28, s92, 0x700e00
	s_addc_u32 s29, s93, 0
	s_add_u32 s30, s92, 0x700f00
	s_addc_u32 s31, s93, 0
	s_add_u32 s34, s92, 0x701000
	s_addc_u32 s35, s93, 0
	s_add_u32 s38, s92, 0x701100
	s_addc_u32 s39, s93, 0
	s_add_u32 s40, s92, 0x701200
	s_addc_u32 s41, s93, 0
	s_add_u32 s44, s92, 0x701300
	s_addc_u32 s45, s93, 0
	s_mov_b32 s58, 1
	v_mov_b32_e32 v16, 0
	s_branch .LBB0_1052

; #define SEAM(k) if (lo <= (k) && (k) + 1 < hi) { xcd_barrier(xb); }
; __device__ __forceinline__ void xcd_barrier(const XcdBarrier& b) {
;     asm volatile("s_waitcnt vmcnt(0)" ::: "memory");
;     __syncthreads();
;     if (threadIdx.x == 0) {
; __global__ void __launch_bounds__(512, 2) fwd_megakernel(Params prm) {
;     ...
;                pg8::EpiGlu E{WSP(bf16_t, WS_CAT), 2048, WSP(bf16_t, WS_BIG + B_YG), 1024, P.in[18]}; pg8::gemm_phase(F.lds, g, S, E); gdn_finalize(F); } SEAM(5)
.LBB0_1125:
	v_readlane_b32 s8, v247, 5
	v_readlane_b32 s9, v247, 6
	s_cmp_gt_i32 s9, 6
	s_cselect_b64 s[0:1], -1, 0
	s_and_b64 s[4:5], s[4:5], s[0:1]
	s_andn2_b64 vcc, exec, s[4:5]
	v_readlane_b32 s10, v247, 7
	v_readlane_b32 s11, v247, 8
	s_cbranch_vccnz .LBB0_1175
	s_waitcnt vmcnt(0)
	v_cmp_eq_u32_e32 vcc, 0, v212
	s_waitcnt vmcnt(0) lgkmcnt(0)
	s_barrier
	v_readlane_b32 s3, v247, 0
	s_nop 3
	s_cmp_lg_u32 s3, 64
	s_cbranch_scc1 .Lew_3
	buffer_wbl2 sc1

; #define PHASE(k) if (lo <= (k) && (k) < hi)
; #define SEAM(k) if (lo <= (k) && (k) + 1 < hi) { xcd_barrier(xb); }
; __device__ __forceinline__ void xcd_barrier(const XcdBarrier& b) {
;     asm volatile("s_waitcnt vmcnt(0)" ::: "memory");
;     __syncthreads();
;     if (threadIdx.x == 0) {
; __global__ void __launch_bounds__(512, 2) fwd_megakernel(Params prm) {
;     ...
;     PHASE(6) { pg8::Gemm g{WSP(bf16_t, WS_CAT), WPTR(W_OUT0), SEQ, 2048, 2048}; pg8::StaticOrder S; S.init(SEQ, 2048, F.G, F.bid); pg8::EpiRaw E{WSP(bf16_t, WS_RAW), 2048, WSP(float, WS_SMALL + SM_SSQ)}; pg8::gemm_phase(F.lds, g, S, E); } SEAM(6)
.LBB0_1218:
	v_readlane_b32 s8, v247, 5
	v_readlane_b32 s9, v247, 6
	s_cmp_gt_i32 s9, 7
	s_cselect_b64 s[0:1], -1, 0
	s_and_b64 s[4:5], s[6:7], s[0:1]
	s_andn2_b64 vcc, exec, s[4:5]
	v_readlane_b32 s10, v247, 7
	v_readlane_b32 s11, v247, 8
	s_cbranch_vccnz .LBB0_1268
	s_waitcnt vmcnt(0)
	v_cmp_eq_u32_e32 vcc, 0, v212
	s_waitcnt vmcnt(0) lgkmcnt(0)
	s_barrier
	v_readlane_b32 s3, v247, 0
	s_nop 3
	s_cmp_lg_u32 s3, 64
	s_cbranch_scc1 .Lew_4
	buffer_wbl2 sc1

; __device__ __forceinline__ unsigned xb_ld(unsigned* p)              { return __hip_atomic_load(p, __ATOMIC_RELAXED, __HIP_MEMORY_SCOPE_AGENT); }
; __device__ __forceinline__ unsigned xb_add(unsigned* p, unsigned v) { return __hip_atomic_fetch_add(p, v, __ATOMIC_RELAXED, __HIP_MEMORY_SCOPE_AGENT); }
; __device__ __forceinline__ void xcd_barrier_complete(unsigned* bar, unsigned x, unsigned& nloc, unsigned& nx) {
;     const unsigned G = gridDim.x * gridDim.y * gridDim.z;
;     unsigned sum, cnt, mine, sp = 0u;
;     for (;;) {
;         sum = 0u; cnt = 0u; mine = 0u;
; #pragma unroll
;         for (unsigned j = 0; j < 16; ++j) { const unsigned c = xb_ld(&bar[XB_XCNT(j)]); sum += c; cnt += (c > 0u) ? 1u : 0u; mine = (j == x) ? c : mine; }
; __device__ __forceinline__ void xcd_barrier(const XcdBarrier& b) {
;     asm volatile("s_waitcnt vmcnt(0)" ::: "memory");
;     __syncthreads();
;     if (threadIdx.x == 0) {
;         unsigned* bar = b.bar;
;         __builtin_amdgcn_s_waitcnt(0);
;         unsigned nloc = b.st[0], nx = b.st[1];
;         if (nloc == 0u) { xcd_barrier_complete(bar, b.x, nloc, nx); b.st[0] = nloc; b.st[1] = nx; }
;         const unsigned old = xb_add(&bar[XB_XSUB(b.x)], 1u);
.LBB0_1276:
	v_readlane_b32 s8, v247, 5
	v_readlane_b32 s9, v247, 6
	s_cmp_gt_i32 s9, 8
	s_cselect_b64 s[0:1], -1, 0
	s_and_b64 s[4:5], s[4:5], s[0:1]
	s_andn2_b64 vcc, exec, s[4:5]
	v_readlane_b32 s10, v247, 7
	v_readlane_b32 s11, v247, 8
	s_cbranch_vccnz .LBB0_1326
	s_waitcnt vmcnt(0)
	v_cmp_eq_u32_e32 vcc, 0, v212
	s_waitcnt vmcnt(0) lgkmcnt(0)
	s_barrier
	v_readlane_b32 s3, v247, 0
	s_nop 3
	s_cmp_lg_u32 s3, 64
	s_cbranch_scc1 .Lew_5
	buffer_wbl2 sc1
.Lew_5:
	s_and_saveexec_b64 s[4:5], vcc
	s_cbranch_execz .LBB0_1325
	s_add_i32 s3, 0, 0x27ff0
	v_mov_b32_e32 v0, s3
	s_waitcnt vmcnt(0) expcnt(0) lgkmcnt(0)
	ds_read_b32 v2, v0
	s_add_i32 s3, 0, 0x27ff4
	v_mov_b32_e32 v0, s3
	ds_read_b32 v0, v0
	s_waitcnt lgkmcnt(1)
	v_cmp_ne_u32_e32 vcc, 0, v2
	s_cbranch_vccnz .LBB0_1293
	v_readlane_b32 s6, v247, 1
	v_readlane_b32 s7, v247, 2
	s_load_dwordx2 s[10:11], s[6:7], 0x4
	s_add_u32 s6, s92, 0x700200
	s_addc_u32 s7, s93, 0
	s_add_u32 s8, s92, 0x700400
	s_addc_u32 s9, s93, 0
	s_waitcnt lgkmcnt(0)
	s_mul_i32 s3, s10, s33
	s_add_u32 s10, s92, 0x700500
	s_mul_i32 s3, s3, s11
	s_addc_u32 s11, s93, 0
	s_add_u32 s12, s92, 0x700600
	s_addc_u32 s13, s93, 0
	s_add_u32 s14, s92, 0x700700
	s_addc_u32 s15, s93, 0
	s_add_u32 s16, s92, 0x700800
	s_addc_u32 s17, s93, 0
	s_add_u32 s18, s92, 0x700900
	s_addc_u32 s19, s93, 0
	s_add_u32 s20, s92, 0x700a00
	s_addc_u32 s21, s93, 0
	s_add_u32 s22, s92, 0x700b00
	s_addc_u32 s23, s93, 0
	s_add_u32 s24, s92, 0x700c00
	s_addc_u32 s25, s93, 0
	s_add_u32 s26, s92, 0x700d00
	s_addc_u32 s27, s93, 0
	s_add_u32 s28, s92, 0x700e00
	s_addc_u32 s29, s93, 0
	s_add_u32 s30, s92, 0x700f00
	s_addc_u32 s31, s93, 0
	s_add_u32 s34, s92, 0x701000
	s_addc_u32 s35, s93, 0
	s_add_u32 s36, s92, 0x701100
	s_addc_u32 s37, s93, 0
	s_add_u32 s38, s92, 0x701200
	s_addc_u32 s39, s93, 0
	s_add_u32 s40, s92, 0x701300
	s_addc_u32 s41, s93, 0
	s_mov_b32 s52, 1
	v_mov_b32_e32 v16, 0
	s_branch .LBB0_1281

; #define PHASE(k) if (lo <= (k) && (k) < hi)
; #define SEAM(k) if (lo <= (k) && (k) + 1 < hi) { xcd_barrier(xb); }
; __device__ __forceinline__ void xcd_barrier(const XcdBarrier& b) {
;     asm volatile("s_waitcnt vmcnt(0)" ::: "memory");
;     __syncthreads();
;     if (threadIdx.x == 0) {
; __global__ void __launch_bounds__(512, 2) fwd_megakernel(Params prm) {
;     ...
;     PHASE(8) { pg8::Gemm g{WSP(bf16_t, WS_H), WPTR(W_GU0), SEQ, 11264, 2048}; pg8::StaticOrder S; S.init(SEQ, 11264, F.G, F.bid); pg8::EpiSwiglu E{WSP(bf16_t, WS_BIG + B_HID), FFH}; pg8::gemm_phase(F.lds, g, S, E); } SEAM(8)
.LBB0_1343:
	v_readlane_b32 s8, v247, 5
	v_readlane_b32 s9, v247, 6
	s_cmp_gt_i32 s9, 9
	s_cselect_b64 s[0:1], -1, 0
	s_and_b64 s[4:5], s[4:5], s[0:1]
	s_andn2_b64 vcc, exec, s[4:5]
	v_readlane_b32 s10, v247, 7
	v_readlane_b32 s11, v247, 8
	s_cbranch_vccnz .LBB0_1393
	s_waitcnt vmcnt(0)
	v_cmp_eq_u32_e32 vcc, 0, v212
	s_waitcnt vmcnt(0) lgkmcnt(0)
	s_barrier
	v_readlane_b32 s3, v247, 0
	s_nop 3
	s_cmp_lg_u32 s3, 64
	s_cbranch_scc1 .Lew_6
	buffer_wbl2 sc1

; #define PHASE(k) if (lo <= (k) && (k) < hi)
; #define SEAM(k) if (lo <= (k) && (k) + 1 < hi) { xcd_barrier(xb); }
; __device__ __forceinline__ void xcd_barrier(const XcdBarrier& b) {
;     asm volatile("s_waitcnt vmcnt(0)" ::: "memory");
;     __syncthreads();
;     if (threadIdx.x == 0) {
; __global__ void __launch_bounds__(512, 2) fwd_megakernel(Params prm) {
;     ...
;     PHASE(9) { pg8::Gemm g{WSP(bf16_t, WS_BIG + B_HID), WPTR(W_DN0), SEQ, 2048, FFH}; pg8::StaticOrder S; S.init(SEQ, 2048, F.G, F.bid); pg8::EpiRaw E{WSP(bf16_t, WS_RAW), 2048, WSP(float, WS_SMALL + SM_SSQ)}; pg8::gemm_phase(F.lds, g, S, E); } SEAM(9)
.LBB0_1440:
	v_readlane_b32 s4, v247, 5
	v_readlane_b32 s5, v247, 6
	s_cmp_gt_i32 s5, 10
	s_cselect_b64 s[0:1], -1, 0
	s_and_b64 s[4:5], s[8:9], s[0:1]
	s_andn2_b64 vcc, exec, s[4:5]
	v_readlane_b32 s6, v247, 7
	v_readlane_b32 s7, v247, 8
	s_cbranch_vccnz .LBB0_1490
	s_waitcnt vmcnt(0)
	v_cmp_eq_u32_e32 vcc, 0, v212
	s_waitcnt vmcnt(0) lgkmcnt(0)
	s_barrier
	v_readlane_b32 s3, v247, 0
	s_nop 3
	s_cmp_lg_u32 s3, 64
	s_cbranch_scc1 .Lew_7
	buffer_wbl2 sc1

; __device__ __forceinline__ unsigned xb_ld(unsigned* p)              { return __hip_atomic_load(p, __ATOMIC_RELAXED, __HIP_MEMORY_SCOPE_AGENT); }
; __device__ __forceinline__ unsigned xb_add(unsigned* p, unsigned v) { return __hip_atomic_fetch_add(p, v, __ATOMIC_RELAXED, __HIP_MEMORY_SCOPE_AGENT); }
; __device__ __forceinline__ void xcd_barrier_complete(unsigned* bar, unsigned x, unsigned& nloc, unsigned& nx) {
;     const unsigned G = gridDim.x * gridDim.y * gridDim.z;
;     unsigned sum, cnt, mine, sp = 0u;
;     for (;;) {
;         sum = 0u; cnt = 0u; mine = 0u;
; #pragma unroll
;         for (unsigned j = 0; j < 16; ++j) { const unsigned c = xb_ld(&bar[XB_XCNT(j)]); sum += c; cnt += (c > 0u) ? 1u : 0u; mine = (j == x) ? c : mine; }
; __device__ __forceinline__ void xcd_barrier(const XcdBarrier& b) {
;     asm volatile("s_waitcnt vmcnt(0)" ::: "memory");
;     __syncthreads();
;     if (threadIdx.x == 0) {
;         unsigned* bar = b.bar;
;         __builtin_amdgcn_s_waitcnt(0);
;         unsigned nloc = b.st[0], nx = b.st[1];
;         if (nloc == 0u) { xcd_barrier_complete(bar, b.x, nloc, nx); b.st[0] = nloc; b.st[1] = nx; }
;         const unsigned old = xb_add(&bar[XB_XSUB(b.x)], 1u);
.LBB0_1512:
	v_readlane_b32 s4, v247, 5
	v_readlane_b32 s5, v247, 6
	s_cmp_gt_i32 s5, 11
	s_cselect_b64 s[0:1], -1, 0
	s_and_b64 s[4:5], s[14:15], s[0:1]
	s_andn2_b64 vcc, exec, s[4:5]
	v_readlane_b32 s6, v247, 7
	v_readlane_b32 s7, v247, 8
	s_cbranch_vccnz .LBB0_1562
	s_waitcnt vmcnt(0)
	v_cmp_eq_u32_e32 vcc, 0, v212
	s_waitcnt vmcnt(0) lgkmcnt(0)
	s_barrier
	v_readlane_b32 s3, v247, 0
	s_nop 3
	s_cmp_lg_u32 s3, 64
	s_cbranch_scc1 .Lew_8
	buffer_wbl2 sc1
.Lew_8:
	s_and_saveexec_b64 s[4:5], vcc
	s_cbranch_execz .LBB0_1561
	s_add_i32 s3, 0, 0x27ff0
	v_mov_b32_e32 v0, s3
	s_waitcnt vmcnt(0) expcnt(0) lgkmcnt(0)
	ds_read_b32 v2, v0
	s_add_i32 s3, 0, 0x27ff4
	v_mov_b32_e32 v0, s3
	ds_read_b32 v0, v0
	s_waitcnt lgkmcnt(1)
	v_cmp_ne_u32_e32 vcc, 0, v2
	s_cbranch_vccnz .LBB0_1529
	v_readlane_b32 s6, v247, 1
	v_readlane_b32 s7, v247, 2
	s_load_dwordx2 s[10:11], s[6:7], 0x4
	s_add_u32 s6, s92, 0x700200
	s_addc_u32 s7, s93, 0
	s_add_u32 s8, s92, 0x700400
	s_addc_u32 s9, s93, 0
	s_waitcnt lgkmcnt(0)
	s_mul_i32 s3, s10, s33
	s_add_u32 s10, s92, 0x700500
	s_mul_i32 s3, s3, s11
	s_addc_u32 s11, s93, 0
	s_add_u32 s12, s92, 0x700600
	s_addc_u32 s13, s93, 0
	s_add_u32 s14, s92, 0x700700
	s_addc_u32 s15, s93, 0
	s_add_u32 s16, s92, 0x700800
	s_addc_u32 s17, s93, 0
	s_add_u32 s18, s92, 0x700900
	s_addc_u32 s19, s93, 0
	s_add_u32 s20, s92, 0x700a00
	s_addc_u32 s21, s93, 0
	s_add_u32 s22, s92, 0x700b00
	s_addc_u32 s23, s93, 0
	s_add_u32 s24, s92, 0x700c00
	s_addc_u32 s25, s93, 0
	s_add_u32 s26, s92, 0x700d00
	s_addc_u32 s27, s93, 0
	s_add_u32 s28, s92, 0x700e00
	s_addc_u32 s29, s93, 0
	s_add_u32 s30, s92, 0x700f00
	s_addc_u32 s31, s93, 0
	s_add_u32 s34, s92, 0x701000
	s_addc_u32 s35, s93, 0
	s_add_u32 s36, s92, 0x701100
	s_addc_u32 s37, s93, 0
	s_add_u32 s38, s92, 0x701200
	s_addc_u32 s39, s93, 0
	s_add_u32 s40, s92, 0x701300
	s_addc_u32 s41, s93, 0
	s_mov_b32 s48, 1
	v_mov_b32_e32 v16, 0
	s_branch .LBB0_1517

; #define PHASE(k) if (lo <= (k) && (k) < hi)
; #define SEAM(k) if (lo <= (k) && (k) + 1 < hi) { xcd_barrier(xb); }
; __device__ __forceinline__ void xcd_barrier(const XcdBarrier& b) {
;     asm volatile("s_waitcnt vmcnt(0)" ::: "memory");
;     __syncthreads();
;     if (threadIdx.x == 0) {
; __global__ void __launch_bounds__(512, 2) fwd_megakernel(Params prm) {
;     ...
;     PHASE(11) { pg8::Gemm g{WSP(bf16_t, WS_H), WPTR(W_IN1), SEQ, 6144, 2048}; pg8::StaticOrder S; S.init(SEQ, 6144, F.G, F.bid); pg8::EpiBf16Store E{WSP(bf16_t, WS_BIG + B_Y), 6144}; pg8::gemm_phase(F.lds, g, S, E); } SEAM(11)
.LBB0_1579:
	v_readlane_b32 s8, v247, 5
	v_readlane_b32 s9, v247, 6
	s_cmp_gt_i32 s9, 12
	s_cselect_b64 s[0:1], -1, 0
	s_and_b64 s[4:5], s[4:5], s[0:1]
	s_andn2_b64 vcc, exec, s[4:5]
	v_readlane_b32 s10, v247, 7
	v_readlane_b32 s11, v247, 8
	s_cbranch_vccnz .LBB0_1629
	s_waitcnt vmcnt(0)
	v_cmp_eq_u32_e32 vcc, 0, v212
	s_waitcnt vmcnt(0) lgkmcnt(0)
	s_barrier
	v_readlane_b32 s3, v247, 0
	s_nop 3
	s_cmp_lg_u32 s3, 64
	s_cbranch_scc1 .Lew_9
	buffer_wbl2 sc1

; #define PHASE(k) if (lo <= (k) && (k) < hi)
; #define SEAM(k) if (lo <= (k) && (k) + 1 < hi) { xcd_barrier(xb); }
; __device__ __forceinline__ void xcd_barrier(const XcdBarrier& b) {
;     asm volatile("s_waitcnt vmcnt(0)" ::: "memory");
;     __syncthreads();
;     if (threadIdx.x == 0) {
; __global__ void __launch_bounds__(512, 2) fwd_megakernel(Params prm) {
;     ...
;     PHASE(12) { if (F.bid == 0 && F.tid < 8) WSP(int, WS_SMALL + SM_PROG)[(8 + F.tid) * 64] = 0; for (int un = F.bid; un < 1024; un += F.G) gla_local_unit(F, un & 3, un >> 2); } SEAM(12)
.LBB0_1649:
	v_readlane_b32 s4, v247, 5
	v_readlane_b32 s5, v247, 6
	s_cmp_gt_i32 s5, 13
	v_readlane_b32 s4, v246, 30
	s_cselect_b64 s[0:1], -1, 0
	v_readlane_b32 s5, v246, 31
	s_and_b64 s[4:5], s[4:5], s[0:1]
	s_andn2_b64 vcc, exec, s[4:5]
	v_readlane_b32 s6, v247, 7
	v_readlane_b32 s7, v247, 8
	s_cbranch_vccnz .LBB0_1699
	s_waitcnt vmcnt(0)
	v_cmp_eq_u32_e32 vcc, 0, v212
	s_waitcnt vmcnt(0) lgkmcnt(0)
	s_barrier
	v_readlane_b32 s3, v247, 0
	s_nop 3
	s_cmp_lg_u32 s3, 64
	s_cbranch_scc1 .Lew_10
	buffer_wbl2 sc1

; #define PHASE(k) if (lo <= (k) && (k) < hi)
; #define SEAM(k) if (lo <= (k) && (k) + 1 < hi) { xcd_barrier(xb); }
; __device__ __forceinline__ void xcd_barrier(const XcdBarrier& b) {
;     asm volatile("s_waitcnt vmcnt(0)" ::: "memory");
;     __syncthreads();
;     if (threadIdx.x == 0) {
; __global__ void __launch_bounds__(512, 2) fwd_megakernel(Params prm) {
;     ...
;     PHASE(13) { if (F.bid < 128) gla_scan_wg(F, F.bid & 3, F.bid >> 2); else if (F.bid < 224) convert_layer1_rest_idle(F, 128, 224); else gla_warm_wg(F, F.bid & 7, (F.bid - 224) >> 3); } SEAM(13)
.LBB0_1851:
	v_readlane_b32 s4, v247, 5
	v_readlane_b32 s5, v247, 6
	s_cmp_gt_i32 s5, 14
	s_cselect_b64 s[0:1], -1, 0
	s_and_b64 s[4:5], s[36:37], s[0:1]
	s_andn2_b64 vcc, exec, s[4:5]
	v_readlane_b32 s6, v247, 7
	v_readlane_b32 s7, v247, 8
	s_cbranch_vccnz .LBB0_1901
	s_waitcnt vmcnt(0)
	v_cmp_eq_u32_e32 vcc, 0, v212
	s_waitcnt vmcnt(0) lgkmcnt(0)
	s_barrier
	v_readlane_b32 s3, v247, 0
	s_nop 3
	s_cmp_lg_u32 s3, 64
	s_cbranch_scc1 .Lew_11
	buffer_wbl2 sc1

; #define PHASE(k) if (lo <= (k) && (k) < hi)
; #define SEAM(k) if (lo <= (k) && (k) + 1 < hi) { xcd_barrier(xb); }
; __device__ __forceinline__ void xcd_barrier(const XcdBarrier& b) {
;     asm volatile("s_waitcnt vmcnt(0)" ::: "memory");
;     __syncthreads();
;     if (threadIdx.x == 0) {
; __global__ void __launch_bounds__(512, 2) fwd_megakernel(Params prm) {
;     ...
;     PHASE(14) { gla_finalize(F); } SEAM(14)
.LBB0_1905:
	v_readlane_b32 s8, v247, 5
	v_readlane_b32 s9, v247, 6
	s_cmp_gt_i32 s9, 15
	s_cselect_b64 s[0:1], -1, 0
	s_and_b64 s[4:5], s[4:5], s[0:1]
	s_andn2_b64 vcc, exec, s[4:5]
	v_readlane_b32 s10, v247, 7
	v_readlane_b32 s11, v247, 8
	s_cbranch_vccnz .LBB0_1955
	s_waitcnt vmcnt(0)
	v_cmp_eq_u32_e32 vcc, 0, v212
	s_waitcnt vmcnt(0) lgkmcnt(0)
	s_barrier
	v_readlane_b32 s3, v247, 0
	s_nop 3
	s_cmp_lg_u32 s3, 64
	s_cbranch_scc1 .Lew_12
	buffer_wbl2 sc1

; #define PHASE(k) if (lo <= (k) && (k) < hi)
; #define SEAM(k) if (lo <= (k) && (k) + 1 < hi) { xcd_barrier(xb); }
; __device__ __forceinline__ void xcd_barrier(const XcdBarrier& b) {
;     asm volatile("s_waitcnt vmcnt(0)" ::: "memory");
;     __syncthreads();
;     if (threadIdx.x == 0) {
; __global__ void __launch_bounds__(512, 2) fwd_megakernel(Params prm) {
;     ...
;     PHASE(15) { pg8::Gemm g{WSP(bf16_t, WS_CAT), WPTR(W_OUT1), SEQ, 2048, 2048}; pg8::StaticOrder S; S.init(SEQ, 2048, F.G, F.bid); pg8::EpiRaw E{WSP(bf16_t, WS_RAW), 2048, WSP(float, WS_SMALL + SM_SSQ)}; pg8::gemm_phase(F.lds, g, S, E); } SEAM(15)
.LBB0_1998:
	v_readlane_b32 s8, v247, 5
	v_readlane_b32 s9, v247, 6
	s_cmp_gt_i32 s9, 16
	s_cselect_b64 s[0:1], -1, 0
	s_and_b64 s[4:5], s[6:7], s[0:1]
	s_andn2_b64 vcc, exec, s[4:5]
	v_readlane_b32 s10, v247, 7
	v_readlane_b32 s11, v247, 8
	s_cbranch_vccnz .LBB0_2048
	s_waitcnt vmcnt(0)
	v_cmp_eq_u32_e32 vcc, 0, v212
	s_waitcnt vmcnt(0) lgkmcnt(0)
	s_barrier
	v_readlane_b32 s3, v247, 0
	s_nop 3
	s_cmp_lg_u32 s3, 64
	s_cbranch_scc1 .Lew_13
	buffer_wbl2 sc1

; #define PHASE(k) if (lo <= (k) && (k) < hi)
; #define SEAM(k) if (lo <= (k) && (k) + 1 < hi) { xcd_barrier(xb); }
; __device__ __forceinline__ void xcd_barrier(const XcdBarrier& b) {
;     asm volatile("s_waitcnt vmcnt(0)" ::: "memory");
;     __syncthreads();
;     if (threadIdx.x == 0) {
; __global__ void __launch_bounds__(512, 2) fwd_megakernel(Params prm) {
;     ...
;     PHASE(16) { RowCfg c{1, 4096, 30, 1, 31, 8192, 6144, 0, 0, 0, P.out, nullptr}; row_phase<true, true, false>(F, c); } SEAM(16)
.LBB0_2056:
	v_readlane_b32 s8, v247, 5
	v_readlane_b32 s9, v247, 6
	s_cmp_gt_i32 s9, 17
	s_cselect_b64 s[0:1], -1, 0
	s_and_b64 s[4:5], s[4:5], s[0:1]
	s_andn2_b64 vcc, exec, s[4:5]
	v_readlane_b32 s10, v247, 7
	v_readlane_b32 s11, v247, 8
	s_cbranch_vccnz .LBB0_2106
	s_waitcnt vmcnt(0)
	v_cmp_eq_u32_e32 vcc, 0, v212
	s_waitcnt vmcnt(0) lgkmcnt(0)
	s_barrier
	v_readlane_b32 s3, v247, 0
	s_nop 3
	s_cmp_lg_u32 s3, 64
	s_cbranch_scc1 .Lew_14
	buffer_wbl2 sc1

; #define PHASE(k) if (lo <= (k) && (k) < hi)
; #define SEAM(k) if (lo <= (k) && (k) + 1 < hi) { xcd_barrier(xb); }
; __device__ __forceinline__ void xcd_barrier(const XcdBarrier& b) {
;     asm volatile("s_waitcnt vmcnt(0)" ::: "memory");
;     __syncthreads();
;     if (threadIdx.x == 0) {
; __global__ void __launch_bounds__(512, 2) fwd_megakernel(Params prm) {
;     ...
;     PHASE(17) { pg8::Gemm g{WSP(bf16_t, WS_H), WPTR(W_GU1), SEQ, 11264, 2048}; pg8::StaticOrder S; S.init(SEQ, 11264, F.G, F.bid); pg8::EpiSwiglu E{WSP(bf16_t, WS_BIG + B_HID), FFH}; pg8::gemm_phase(F.lds, g, S, E); } SEAM(17)
.LBB0_2123:
	v_readlane_b32 s8, v247, 5
	v_readlane_b32 s9, v247, 6
	s_cmp_gt_i32 s9, 18
	s_cselect_b64 s[0:1], -1, 0
	s_and_b64 s[4:5], s[4:5], s[0:1]
	s_andn2_b64 vcc, exec, s[4:5]
	v_readlane_b32 s10, v247, 7
	v_readlane_b32 s11, v247, 8
	s_cbranch_vccnz .LBB0_2173
	s_waitcnt vmcnt(0)
	v_cmp_eq_u32_e32 vcc, 0, v212
	s_waitcnt vmcnt(0) lgkmcnt(0)
	s_barrier
	v_readlane_b32 s3, v247, 0
	s_nop 3
	s_cmp_lg_u32 s3, 64
	s_cbranch_scc1 .Lew_15
	buffer_wbl2 sc1

; #define PHASE(k) if (lo <= (k) && (k) < hi)
; #define SEAM(k) if (lo <= (k) && (k) + 1 < hi) { xcd_barrier(xb); }
; __device__ __forceinline__ void xcd_barrier(const XcdBarrier& b) {
;     asm volatile("s_waitcnt vmcnt(0)" ::: "memory");
;     __syncthreads();
;     if (threadIdx.x == 0) {
; __global__ void __launch_bounds__(512, 2) fwd_megakernel(Params prm) {
;     ...
;     PHASE(18) { pg8::Gemm g{WSP(bf16_t, WS_BIG + B_HID), WPTR(W_DN1), SEQ, 2048, FFH}; pg8::StaticOrder S; S.init(SEQ, 2048, F.G, F.bid); pg8::EpiRaw E{WSP(bf16_t, WS_RAW), 2048, WSP(float, WS_SMALL + SM_SSQ)}; pg8::gemm_phase(F.lds, g, S, E); } SEAM(18)
.LBB0_2220:
	v_readlane_b32 s4, v247, 5
	v_readlane_b32 s5, v247, 6
	s_cmp_gt_i32 s5, 19
	s_cselect_b64 s[0:1], -1, 0
	s_and_b64 s[4:5], s[8:9], s[0:1]
	s_andn2_b64 vcc, exec, s[4:5]
	v_readlane_b32 s6, v247, 7
	v_readlane_b32 s7, v247, 8
	s_cbranch_vccnz .LBB0_2270
	s_waitcnt vmcnt(0)
	v_cmp_eq_u32_e32 vcc, 0, v212
	s_waitcnt vmcnt(0) lgkmcnt(0)
	s_barrier
	v_readlane_b32 s3, v247, 0
	s_nop 3
	s_cmp_lg_u32 s3, 64
	s_cbranch_scc1 .Lew_16
	buffer_wbl2 sc1
